# w_out and P.VW fused epilogues: the 16 residual-tile loads issued right after the K-loop instead of after the publish step
# speedup vs baseline: 1.0057x; 1.0057x over previous
.LBB0_741:
	s_add_u32 s12, s36, 0xfff80080
	s_addc_u32 s13, s37, -1
	s_add_i32 s14, 0, 0x10000
	s_cmp_eq_u32 s11, 28
	s_cselect_b32 s63, s5, s13
	s_cselect_b32 s62, s6, s12
	s_cselect_b32 s39, s7, s10
	s_cselect_b32 s38, s8, s9
	s_add_i32 s15, 0, 0x14000
	v_add_u32_e32 v144, s14, v230
	v_add_u32_e32 v160, s15, v230
	ds_read_b128 v[124:127], v144
	ds_read_b128 v[128:131], v144 offset:1024
	ds_read_b128 v[136:139], v144 offset:2048
	ds_read_b128 v[144:147], v144 offset:3072
	ds_read_b128 v[148:151], v160
	ds_read_b128 v[152:155], v160 offset:1024
	ds_read_b128 v[156:159], v160 offset:2048
	ds_read_b128 v[160:163], v160 offset:3072
	v_lshl_add_u64 v[196:197], s[36:37], 0, v[222:223]
	s_add_i32 m0, s21, 0xc000
	ds_read_b128 v[164:167], v243
	ds_read_b128 v[168:171], v243 offset:1024
	ds_read_b128 v[172:175], v243 offset:2048
	ds_read_b128 v[176:179], v243 offset:3072
	ds_read_b128 v[180:183], v243 offset:4096
	ds_read_b128 v[184:187], v243 offset:5120
	ds_read_b128 v[188:191], v243 offset:6144
	ds_read_b128 v[192:195], v243 offset:7168
	global_load_lds_dwordx4 v[196:197], off
	v_lshl_add_u64 v[196:197], s[36:37], 0, v[220:221]
	s_add_i32 m0, s21, 0xe000
	s_nop 0
	global_load_lds_dwordx4 v[196:197], off
	s_waitcnt vmcnt(8)
	s_waitcnt lgkmcnt(0)
	s_barrier
	s_setprio 1
	s_waitcnt lgkmcnt(0)
	v_mfma_f32_16x16x32_bf16 v[140:143], v[124:127], v[164:167], v[140:143]
	v_mfma_f32_16x16x32_bf16 v[132:135], v[136:139], v[164:167], v[132:135]
	v_mfma_f32_16x16x32_bf16 v[112:115], v[124:127], v[172:175], v[112:115]
	v_mfma_f32_16x16x32_bf16 v[108:111], v[136:139], v[172:175], v[108:111]
	v_mfma_f32_16x16x32_bf16 v[96:99], v[124:127], v[180:183], v[96:99]
	v_mfma_f32_16x16x32_bf16 v[92:95], v[136:139], v[180:183], v[92:95]
	v_mfma_f32_16x16x32_bf16 v[80:83], v[124:127], v[188:191], v[80:83]
	v_mfma_f32_16x16x32_bf16 v[76:79], v[136:139], v[188:191], v[76:79]
	v_mfma_f32_16x16x32_bf16 v[140:143], v[128:131], v[168:171], v[140:143]
	v_mfma_f32_16x16x32_bf16 v[132:135], v[144:147], v[168:171], v[132:135]
	v_mfma_f32_16x16x32_bf16 v[112:115], v[128:131], v[176:179], v[112:115]
	v_mfma_f32_16x16x32_bf16 v[108:111], v[144:147], v[176:179], v[108:111]
	v_mfma_f32_16x16x32_bf16 v[96:99], v[128:131], v[184:187], v[96:99]
	v_mfma_f32_16x16x32_bf16 v[92:95], v[144:147], v[184:187], v[92:95]
	v_mfma_f32_16x16x32_bf16 v[80:83], v[128:131], v[192:195], v[80:83]
	v_mfma_f32_16x16x32_bf16 v[76:79], v[144:147], v[192:195], v[76:79]
	s_setprio 0
	s_setprio 1
	v_mfma_f32_16x16x32_bf16 v[120:123], v[148:151], v[164:167], v[120:123]
	v_mfma_f32_16x16x32_bf16 v[116:119], v[156:159], v[164:167], v[116:119]
	v_mfma_f32_16x16x32_bf16 v[104:107], v[148:151], v[172:175], v[104:107]
	v_mfma_f32_16x16x32_bf16 v[100:103], v[156:159], v[172:175], v[100:103]
	v_mfma_f32_16x16x32_bf16 v[88:91], v[148:151], v[180:183], v[88:91]
	v_mfma_f32_16x16x32_bf16 v[84:87], v[156:159], v[180:183], v[84:87]
	v_mfma_f32_16x16x32_bf16 v[72:75], v[148:151], v[188:191], v[72:75]
	v_mfma_f32_16x16x32_bf16 v[68:71], v[156:159], v[188:191], v[68:71]
	v_mfma_f32_16x16x32_bf16 v[120:123], v[152:155], v[168:171], v[120:123]
	v_mfma_f32_16x16x32_bf16 v[116:119], v[160:163], v[168:171], v[116:119]
	v_mfma_f32_16x16x32_bf16 v[104:107], v[152:155], v[176:179], v[104:107]
	v_mfma_f32_16x16x32_bf16 v[100:103], v[160:163], v[176:179], v[100:103]
	v_mfma_f32_16x16x32_bf16 v[88:91], v[152:155], v[184:187], v[88:91]
	v_mfma_f32_16x16x32_bf16 v[84:87], v[160:163], v[184:187], v[84:87]
	v_mfma_f32_16x16x32_bf16 v[72:75], v[152:155], v[192:195], v[72:75]
	v_mfma_f32_16x16x32_bf16 v[68:71], v[160:163], v[192:195], v[68:71]
	s_setprio 0
	s_barrier
	s_add_i32 s12, s14, s82
	v_lshl_add_u64 v[196:197], s[38:39], 0, v[2:3]
	s_mov_b32 m0, s12
	ds_read_b128 v[164:167], v243 offset:16384
	ds_read_b128 v[168:171], v243 offset:17408
	ds_read_b128 v[172:175], v243 offset:18432
	ds_read_b128 v[176:179], v243 offset:19456
	ds_read_b128 v[180:183], v243 offset:20480
	ds_read_b128 v[184:187], v243 offset:21504
	ds_read_b128 v[188:191], v243 offset:22528
	ds_read_b128 v[192:195], v243 offset:23552
	global_load_lds_dwordx4 v[196:197], off
	s_add_i32 m0, s12, 0x2000
	s_add_u32 s12, s38, 0x80000
	v_lshl_add_u64 v[198:199], s[38:39], 0, v[218:219]
	s_addc_u32 s13, s39, 0
	s_add_i32 s14, s15, s82
	global_load_lds_dwordx4 v[198:199], off
	v_lshl_add_u64 v[200:201], s[12:13], 0, v[2:3]
	s_mov_b32 m0, s14
	v_lshl_add_u64 v[202:203], s[62:63], 0, v[216:217]
	global_load_lds_dwordx4 v[200:201], off
	v_lshl_add_u64 v[200:201], s[12:13], 0, v[218:219]
	s_add_i32 m0, s14, 0x2000
	s_nop 0
	global_load_lds_dwordx4 v[200:201], off
	v_lshl_add_u64 v[200:201], s[62:63], 0, v[0:1]
	s_mov_b32 m0, s21
	s_nop 0
	global_load_lds_dwordx4 v[200:201], off
	s_mov_b32 m0, s83
	s_nop 0
	global_load_lds_dwordx4 v[202:203], off
	s_waitcnt vmcnt(8)
	s_waitcnt lgkmcnt(0)
	s_barrier
	s_setprio 1
	s_waitcnt lgkmcnt(0)
	v_mfma_f32_16x16x32_bf16 v[64:67], v[124:127], v[164:167], v[64:67]
	v_mfma_f32_16x16x32_bf16 v[60:63], v[136:139], v[164:167], v[60:63]
	v_mfma_f32_16x16x32_bf16 v[48:51], v[124:127], v[172:175], v[48:51]
	v_mfma_f32_16x16x32_bf16 v[44:47], v[136:139], v[172:175], v[44:47]
	v_mfma_f32_16x16x32_bf16 v[32:35], v[124:127], v[180:183], v[32:35]
	v_mfma_f32_16x16x32_bf16 v[28:31], v[136:139], v[180:183], v[28:31]
	v_mfma_f32_16x16x32_bf16 v[16:19], v[124:127], v[188:191], v[16:19]
	v_mfma_f32_16x16x32_bf16 v[12:15], v[136:139], v[188:191], v[12:15]
	v_mfma_f32_16x16x32_bf16 v[64:67], v[128:131], v[168:171], v[64:67]
	v_mfma_f32_16x16x32_bf16 v[60:63], v[144:147], v[168:171], v[60:63]
	v_mfma_f32_16x16x32_bf16 v[48:51], v[128:131], v[176:179], v[48:51]
	v_mfma_f32_16x16x32_bf16 v[44:47], v[144:147], v[176:179], v[44:47]
	v_mfma_f32_16x16x32_bf16 v[32:35], v[128:131], v[184:187], v[32:35]
	v_mfma_f32_16x16x32_bf16 v[28:31], v[144:147], v[184:187], v[28:31]
	v_mfma_f32_16x16x32_bf16 v[16:19], v[128:131], v[192:195], v[16:19]
	v_mfma_f32_16x16x32_bf16 v[12:15], v[144:147], v[192:195], v[12:15]
	s_setprio 0
	s_setprio 1
	v_mfma_f32_16x16x32_bf16 v[56:59], v[148:151], v[164:167], v[56:59]
	v_mfma_f32_16x16x32_bf16 v[52:55], v[156:159], v[164:167], v[52:55]
	v_mfma_f32_16x16x32_bf16 v[40:43], v[148:151], v[172:175], v[40:43]
	v_mfma_f32_16x16x32_bf16 v[36:39], v[156:159], v[172:175], v[36:39]
	v_mfma_f32_16x16x32_bf16 v[24:27], v[148:151], v[180:183], v[24:27]
	v_mfma_f32_16x16x32_bf16 v[20:23], v[156:159], v[180:183], v[20:23]
	v_mfma_f32_16x16x32_bf16 v[8:11], v[148:151], v[188:191], v[8:11]
	v_mfma_f32_16x16x32_bf16 v[4:7], v[156:159], v[188:191], v[4:7]
	v_mfma_f32_16x16x32_bf16 v[56:59], v[152:155], v[168:171], v[56:59]
	v_mfma_f32_16x16x32_bf16 v[52:55], v[160:163], v[168:171], v[52:55]
	v_mfma_f32_16x16x32_bf16 v[40:43], v[152:155], v[176:179], v[40:43]
	v_mfma_f32_16x16x32_bf16 v[36:39], v[160:163], v[176:179], v[36:39]
	v_mfma_f32_16x16x32_bf16 v[24:27], v[152:155], v[184:187], v[24:27]
	v_mfma_f32_16x16x32_bf16 v[20:23], v[160:163], v[184:187], v[20:23]
	v_mfma_f32_16x16x32_bf16 v[8:11], v[152:155], v[192:195], v[8:11]
	v_mfma_f32_16x16x32_bf16 v[4:7], v[160:163], v[192:195], v[4:7]
	s_setprio 0
	s_barrier
	s_add_i32 s14, 0, 0x18000
	s_add_i32 s15, 0, 0x1c000
	v_add_u32_e32 v144, s14, v230
	v_add_u32_e32 v160, s15, v230
	ds_read_b128 v[124:127], v144
	ds_read_b128 v[128:131], v144 offset:1024
	ds_read_b128 v[136:139], v144 offset:2048
	ds_read_b128 v[144:147], v144 offset:3072
	ds_read_b128 v[148:151], v160
	ds_read_b128 v[152:155], v160 offset:1024
	ds_read_b128 v[156:159], v160 offset:2048
	ds_read_b128 v[160:163], v160 offset:3072
	s_add_u32 s12, s62, 0x80000
	s_addc_u32 s13, s63, 0
	s_mov_b32 m0, s84
	v_lshl_add_u64 v[204:205], s[12:13], 0, v[0:1]
	ds_read_b128 v[164:167], v243 offset:32768
	ds_read_b128 v[168:171], v243 offset:33792
	ds_read_b128 v[172:175], v243 offset:34816
	ds_read_b128 v[176:179], v243 offset:35840
	ds_read_b128 v[180:183], v243 offset:36864
	ds_read_b128 v[184:187], v243 offset:37888
	ds_read_b128 v[188:191], v243 offset:38912
	ds_read_b128 v[192:195], v243 offset:39936
	global_load_lds_dwordx4 v[204:205], off
	v_lshl_add_u64 v[204:205], s[12:13], 0, v[216:217]
	s_mov_b32 m0, s85
	s_nop 0
	global_load_lds_dwordx4 v[204:205], off
	s_waitcnt vmcnt(8)
	s_waitcnt lgkmcnt(0)
	s_barrier
	s_setprio 1
	s_waitcnt lgkmcnt(0)
	v_mfma_f32_16x16x32_bf16 v[140:143], v[124:127], v[164:167], v[140:143]
	v_mfma_f32_16x16x32_bf16 v[132:135], v[136:139], v[164:167], v[132:135]
	v_mfma_f32_16x16x32_bf16 v[112:115], v[124:127], v[172:175], v[112:115]
	v_mfma_f32_16x16x32_bf16 v[108:111], v[136:139], v[172:175], v[108:111]
	v_mfma_f32_16x16x32_bf16 v[96:99], v[124:127], v[180:183], v[96:99]
	v_mfma_f32_16x16x32_bf16 v[92:95], v[136:139], v[180:183], v[92:95]
	v_mfma_f32_16x16x32_bf16 v[80:83], v[124:127], v[188:191], v[80:83]
	v_mfma_f32_16x16x32_bf16 v[76:79], v[136:139], v[188:191], v[76:79]
	v_mfma_f32_16x16x32_bf16 v[140:143], v[128:131], v[168:171], v[140:143]
	v_mfma_f32_16x16x32_bf16 v[132:135], v[144:147], v[168:171], v[132:135]
	v_mfma_f32_16x16x32_bf16 v[112:115], v[128:131], v[176:179], v[112:115]
	v_mfma_f32_16x16x32_bf16 v[108:111], v[144:147], v[176:179], v[108:111]
	v_mfma_f32_16x16x32_bf16 v[96:99], v[128:131], v[184:187], v[96:99]
	v_mfma_f32_16x16x32_bf16 v[92:95], v[144:147], v[184:187], v[92:95]
	v_mfma_f32_16x16x32_bf16 v[80:83], v[128:131], v[192:195], v[80:83]
	v_mfma_f32_16x16x32_bf16 v[76:79], v[144:147], v[192:195], v[76:79]
	s_setprio 0
	s_setprio 1
	v_mfma_f32_16x16x32_bf16 v[120:123], v[148:151], v[164:167], v[120:123]
	v_mfma_f32_16x16x32_bf16 v[116:119], v[156:159], v[164:167], v[116:119]
	v_mfma_f32_16x16x32_bf16 v[104:107], v[148:151], v[172:175], v[104:107]
	v_mfma_f32_16x16x32_bf16 v[100:103], v[156:159], v[172:175], v[100:103]
	v_mfma_f32_16x16x32_bf16 v[88:91], v[148:151], v[180:183], v[88:91]
	v_mfma_f32_16x16x32_bf16 v[84:87], v[156:159], v[180:183], v[84:87]
	v_mfma_f32_16x16x32_bf16 v[72:75], v[148:151], v[188:191], v[72:75]
	v_mfma_f32_16x16x32_bf16 v[68:71], v[156:159], v[188:191], v[68:71]
	v_mfma_f32_16x16x32_bf16 v[120:123], v[152:155], v[168:171], v[120:123]
	v_mfma_f32_16x16x32_bf16 v[116:119], v[160:163], v[168:171], v[116:119]
	v_mfma_f32_16x16x32_bf16 v[104:107], v[152:155], v[176:179], v[104:107]
	v_mfma_f32_16x16x32_bf16 v[100:103], v[160:163], v[176:179], v[100:103]
	v_mfma_f32_16x16x32_bf16 v[88:91], v[152:155], v[184:187], v[88:91]
	v_mfma_f32_16x16x32_bf16 v[84:87], v[160:163], v[184:187], v[84:87]
	v_mfma_f32_16x16x32_bf16 v[72:75], v[152:155], v[192:195], v[72:75]
	v_mfma_f32_16x16x32_bf16 v[68:71], v[160:163], v[192:195], v[68:71]
	s_setprio 0
	s_barrier
	s_add_i32 s12, s14, s82
	v_lshl_add_u64 v[196:197], v[196:197], 0, s[68:69]
	s_mov_b32 m0, s12
	ds_read_b128 v[164:167], v243 offset:49152
	ds_read_b128 v[168:171], v243 offset:50176
	ds_read_b128 v[172:175], v243 offset:51200
	ds_read_b128 v[176:179], v243 offset:52224
	ds_read_b128 v[180:183], v243 offset:53248
	ds_read_b128 v[184:187], v243 offset:54272
	ds_read_b128 v[188:191], v243 offset:55296
	ds_read_b128 v[192:195], v243 offset:56320
	global_load_lds_dwordx4 v[196:197], off
	s_add_i32 m0, s12, 0x2000
	s_add_u32 s12, s38, 0x80080
	v_lshl_add_u64 v[196:197], v[198:199], 0, s[68:69]
	s_addc_u32 s13, s39, 0
	s_add_i32 s14, s15, s82
	global_load_lds_dwordx4 v[196:197], off
	v_lshl_add_u64 v[196:197], s[12:13], 0, v[2:3]
	s_mov_b32 m0, s14
	s_nop 0
	global_load_lds_dwordx4 v[196:197], off
	v_lshl_add_u64 v[196:197], s[12:13], 0, v[218:219]
	s_add_i32 m0, s14, 0x2000
	s_nop 0
	global_load_lds_dwordx4 v[196:197], off
	v_lshl_add_u64 v[196:197], v[200:201], 0, s[68:69]
	s_mov_b32 m0, s89
	s_nop 0
	global_load_lds_dwordx4 v[196:197], off
	v_lshl_add_u64 v[196:197], v[202:203], 0, s[68:69]
	s_mov_b32 m0, s90
	s_nop 0
	global_load_lds_dwordx4 v[196:197], off
	s_waitcnt vmcnt(8)
	s_waitcnt lgkmcnt(0)
	s_barrier
	s_setprio 1
	s_waitcnt lgkmcnt(0)
	v_mfma_f32_16x16x32_bf16 v[64:67], v[124:127], v[164:167], v[64:67]
	v_mfma_f32_16x16x32_bf16 v[60:63], v[136:139], v[164:167], v[60:63]
	v_mfma_f32_16x16x32_bf16 v[48:51], v[124:127], v[172:175], v[48:51]
	v_mfma_f32_16x16x32_bf16 v[44:47], v[136:139], v[172:175], v[44:47]
	v_mfma_f32_16x16x32_bf16 v[32:35], v[124:127], v[180:183], v[32:35]
	v_mfma_f32_16x16x32_bf16 v[28:31], v[136:139], v[180:183], v[28:31]
	v_mfma_f32_16x16x32_bf16 v[16:19], v[124:127], v[188:191], v[16:19]
	v_mfma_f32_16x16x32_bf16 v[12:15], v[136:139], v[188:191], v[12:15]
	v_mfma_f32_16x16x32_bf16 v[64:67], v[128:131], v[168:171], v[64:67]
	v_mfma_f32_16x16x32_bf16 v[60:63], v[144:147], v[168:171], v[60:63]
	v_mfma_f32_16x16x32_bf16 v[48:51], v[128:131], v[176:179], v[48:51]
	v_mfma_f32_16x16x32_bf16 v[44:47], v[144:147], v[176:179], v[44:47]
	v_mfma_f32_16x16x32_bf16 v[32:35], v[128:131], v[184:187], v[32:35]
	v_mfma_f32_16x16x32_bf16 v[28:31], v[144:147], v[184:187], v[28:31]
	v_mfma_f32_16x16x32_bf16 v[16:19], v[128:131], v[192:195], v[16:19]
	v_mfma_f32_16x16x32_bf16 v[12:15], v[144:147], v[192:195], v[12:15]
	s_setprio 0
	s_setprio 1
	v_mfma_f32_16x16x32_bf16 v[56:59], v[148:151], v[164:167], v[56:59]
	v_mfma_f32_16x16x32_bf16 v[52:55], v[156:159], v[164:167], v[52:55]
	v_mfma_f32_16x16x32_bf16 v[40:43], v[148:151], v[172:175], v[40:43]
	v_mfma_f32_16x16x32_bf16 v[36:39], v[156:159], v[172:175], v[36:39]
	v_mfma_f32_16x16x32_bf16 v[24:27], v[148:151], v[180:183], v[24:27]
	v_mfma_f32_16x16x32_bf16 v[20:23], v[156:159], v[180:183], v[20:23]
	v_mfma_f32_16x16x32_bf16 v[8:11], v[148:151], v[188:191], v[8:11]
	v_mfma_f32_16x16x32_bf16 v[4:7], v[156:159], v[188:191], v[4:7]
	v_mfma_f32_16x16x32_bf16 v[56:59], v[152:155], v[168:171], v[56:59]
	v_mfma_f32_16x16x32_bf16 v[52:55], v[160:163], v[168:171], v[52:55]
	v_mfma_f32_16x16x32_bf16 v[40:43], v[152:155], v[176:179], v[40:43]
	v_mfma_f32_16x16x32_bf16 v[36:39], v[160:163], v[176:179], v[36:39]
	v_mfma_f32_16x16x32_bf16 v[24:27], v[152:155], v[184:187], v[24:27]
	v_mfma_f32_16x16x32_bf16 v[20:23], v[160:163], v[184:187], v[20:23]
	v_mfma_f32_16x16x32_bf16 v[8:11], v[152:155], v[192:195], v[8:11]
	v_mfma_f32_16x16x32_bf16 v[4:7], v[160:163], v[192:195], v[4:7]
	s_setprio 0
	s_barrier
	s_add_i32 s11, s11, 2
	s_add_u32 s9, s9, 0x100
	s_addc_u32 s10, s10, 0
	s_add_u32 s36, s36, 0x100
	s_addc_u32 s37, s37, 0
	s_cmp_gt_u32 s11, 29
	s_cbranch_scc0 .LBB0_741
	s_lshl_b32 s98, s54, 8
	s_or_b32 s98, s98, s88
	s_lshl_b32 s99, s4, 8
	s_add_i32 s99, s99, s87
	v_ashrrev_i32_e32 v136, 1, v234
	v_and_b32_e32 v137, 15, v234
	v_and_b32_e32 v136, -8, v136
	v_add_u32_e32 v137, s99, v137
	v_add_u32_e32 v136, s98, v136
	v_lshlrev_b32_e32 v136, 1, v136
	v_lshl_add_u32 v212, v137, 12, v136
	global_load_dwordx4 v[208:211], v212, s[26:27]
	global_load_dwordx4 v[204:207], v212, s[26:27] offset:256
	s_add_u32 s100, s26, 0x10000
	s_addc_u32 s101, s27, 0
	global_load_dwordx4 v[200:203], v212, s[100:101]
	global_load_dwordx4 v[196:199], v212, s[100:101] offset:256
	s_add_u32 s100, s26, 0x20000
	s_addc_u32 s101, s27, 0
	global_load_dwordx4 v[192:195], v212, s[100:101]
	global_load_dwordx4 v[188:191], v212, s[100:101] offset:256
	s_add_u32 s100, s26, 0x30000
	s_addc_u32 s101, s27, 0
	global_load_dwordx4 v[184:187], v212, s[100:101]
	global_load_dwordx4 v[180:183], v212, s[100:101] offset:256
	s_add_u32 s100, s26, 0x80000
	s_addc_u32 s101, s27, 0
	global_load_dwordx4 v[176:179], v212, s[100:101]
	global_load_dwordx4 v[172:175], v212, s[100:101] offset:256
	s_add_u32 s100, s26, 0x90000
	s_addc_u32 s101, s27, 0
	global_load_dwordx4 v[168:171], v212, s[100:101]
	global_load_dwordx4 v[164:167], v212, s[100:101] offset:256
	s_add_u32 s100, s26, 0xa0000
	s_addc_u32 s101, s27, 0
	global_load_dwordx4 v[160:163], v212, s[100:101]
	global_load_dwordx4 v[156:159], v212, s[100:101] offset:256
	s_add_u32 s100, s26, 0xb0000
	s_addc_u32 s101, s27, 0
	global_load_dwordx4 v[152:155], v212, s[100:101]
	global_load_dwordx4 v[148:151], v212, s[100:101] offset:256
	s_and_b64 vcc, exec, s[46:47]
	s_cbranch_vccz .LBB0_744
	s_barrier

.LBB0_764:
	s_or_b64 exec, exec, s[62:63]
	s_lshl_b32 s4, s54, 8
	v_ashrrev_i32_e32 v124, 1, v246
	v_and_b32_e32 v248, 15, v246
	v_and_b32_e32 v124, -8, v124
	s_or_b32 s4, s4, s88
	v_add_u32_e32 v226, s4, v124
	v_ashrrev_i32_e32 v227, 31, v226
	v_lshl_add_u64 v[128:129], v[226:227], 2, s[40:41]
	global_load_dwordx4 v[136:139], v[128:129], off offset:16
	global_load_dwordx4 v[144:147], v[128:129], off
	s_waitcnt lgkmcnt(0)
	global_load_dwordx4 v[124:127], v[128:129], off offset:528
	s_nop 0
	global_load_dwordx4 v[128:131], v[128:129], off offset:512
	s_nop 0
	s_nop 0
	v_ashrrev_i32_e32 v214, 3, v246
	v_and_b32_e32 v214, -4, v214
	v_lshl_add_u64 v[212:213], s[42:43], 0, v[224:225]
	v_ashrrev_i32_e32 v215, 31, v214
	v_lshl_add_u64 v[228:229], v[214:215], 2, v[212:213]
	s_movk_i32 s4, 0x4e20
	s_branch .LBB0_767

.LBB0_947:
	s_add_u32 s12, s38, 0xfffc0080
	s_addc_u32 s13, s39, -1
	s_add_i32 s14, 0, 0x10000
	s_cmp_eq_u32 s11, 12
	s_cselect_b32 s57, s5, s13
	s_cselect_b32 s56, s6, s12
	s_cselect_b32 s41, s7, s10
	s_cselect_b32 s40, s8, s9
	s_add_i32 s15, 0, 0x14000
	v_add_u32_e32 v144, s14, v230
	v_add_u32_e32 v160, s15, v230
	ds_read_b128 v[124:127], v144
	ds_read_b128 v[128:131], v144 offset:1024
	ds_read_b128 v[136:139], v144 offset:2048
	ds_read_b128 v[144:147], v144 offset:3072
	ds_read_b128 v[148:151], v160
	ds_read_b128 v[152:155], v160 offset:1024
	ds_read_b128 v[156:159], v160 offset:2048
	ds_read_b128 v[160:163], v160 offset:3072
	v_lshl_add_u64 v[196:197], s[38:39], 0, v[222:223]
	s_add_i32 m0, s71, 0xc000
	ds_read_b128 v[164:167], v243
	ds_read_b128 v[168:171], v243 offset:1024
	ds_read_b128 v[172:175], v243 offset:2048
	ds_read_b128 v[176:179], v243 offset:3072
	ds_read_b128 v[180:183], v243 offset:4096
	ds_read_b128 v[184:187], v243 offset:5120
	ds_read_b128 v[188:191], v243 offset:6144
	ds_read_b128 v[192:195], v243 offset:7168
	global_load_lds_dwordx4 v[196:197], off
	v_lshl_add_u64 v[196:197], s[38:39], 0, v[220:221]
	s_add_i32 m0, s71, 0xe000
	s_nop 0
	global_load_lds_dwordx4 v[196:197], off
	s_waitcnt vmcnt(8)
	s_waitcnt lgkmcnt(0)
	s_barrier
	s_setprio 1
	s_waitcnt lgkmcnt(0)
	v_mfma_f32_16x16x32_bf16 v[140:143], v[124:127], v[164:167], v[140:143]
	v_mfma_f32_16x16x32_bf16 v[132:135], v[136:139], v[164:167], v[132:135]
	v_mfma_f32_16x16x32_bf16 v[112:115], v[124:127], v[172:175], v[112:115]
	v_mfma_f32_16x16x32_bf16 v[108:111], v[136:139], v[172:175], v[108:111]
	v_mfma_f32_16x16x32_bf16 v[96:99], v[124:127], v[180:183], v[96:99]
	v_mfma_f32_16x16x32_bf16 v[92:95], v[136:139], v[180:183], v[92:95]
	v_mfma_f32_16x16x32_bf16 v[80:83], v[124:127], v[188:191], v[80:83]
	v_mfma_f32_16x16x32_bf16 v[76:79], v[136:139], v[188:191], v[76:79]
	v_mfma_f32_16x16x32_bf16 v[140:143], v[128:131], v[168:171], v[140:143]
	v_mfma_f32_16x16x32_bf16 v[132:135], v[144:147], v[168:171], v[132:135]
	v_mfma_f32_16x16x32_bf16 v[112:115], v[128:131], v[176:179], v[112:115]
	v_mfma_f32_16x16x32_bf16 v[108:111], v[144:147], v[176:179], v[108:111]
	v_mfma_f32_16x16x32_bf16 v[96:99], v[128:131], v[184:187], v[96:99]
	v_mfma_f32_16x16x32_bf16 v[92:95], v[144:147], v[184:187], v[92:95]
	v_mfma_f32_16x16x32_bf16 v[80:83], v[128:131], v[192:195], v[80:83]
	v_mfma_f32_16x16x32_bf16 v[76:79], v[144:147], v[192:195], v[76:79]
	s_setprio 0
	s_setprio 1
	v_mfma_f32_16x16x32_bf16 v[120:123], v[148:151], v[164:167], v[120:123]
	v_mfma_f32_16x16x32_bf16 v[116:119], v[156:159], v[164:167], v[116:119]
	v_mfma_f32_16x16x32_bf16 v[104:107], v[148:151], v[172:175], v[104:107]
	v_mfma_f32_16x16x32_bf16 v[100:103], v[156:159], v[172:175], v[100:103]
	v_mfma_f32_16x16x32_bf16 v[88:91], v[148:151], v[180:183], v[88:91]
	v_mfma_f32_16x16x32_bf16 v[84:87], v[156:159], v[180:183], v[84:87]
	v_mfma_f32_16x16x32_bf16 v[72:75], v[148:151], v[188:191], v[72:75]
	v_mfma_f32_16x16x32_bf16 v[68:71], v[156:159], v[188:191], v[68:71]
	v_mfma_f32_16x16x32_bf16 v[120:123], v[152:155], v[168:171], v[120:123]
	v_mfma_f32_16x16x32_bf16 v[116:119], v[160:163], v[168:171], v[116:119]
	v_mfma_f32_16x16x32_bf16 v[104:107], v[152:155], v[176:179], v[104:107]
	v_mfma_f32_16x16x32_bf16 v[100:103], v[160:163], v[176:179], v[100:103]
	v_mfma_f32_16x16x32_bf16 v[88:91], v[152:155], v[184:187], v[88:91]
	v_mfma_f32_16x16x32_bf16 v[84:87], v[160:163], v[184:187], v[84:87]
	v_mfma_f32_16x16x32_bf16 v[72:75], v[152:155], v[192:195], v[72:75]
	v_mfma_f32_16x16x32_bf16 v[68:71], v[160:163], v[192:195], v[68:71]
	s_setprio 0
	s_barrier
	s_add_i32 s12, s14, s70
	v_lshl_add_u64 v[196:197], s[40:41], 0, v[2:3]
	s_mov_b32 m0, s12
	ds_read_b128 v[164:167], v243 offset:16384
	ds_read_b128 v[168:171], v243 offset:17408
	ds_read_b128 v[172:175], v243 offset:18432
	ds_read_b128 v[176:179], v243 offset:19456
	ds_read_b128 v[180:183], v243 offset:20480
	ds_read_b128 v[184:187], v243 offset:21504
	ds_read_b128 v[188:191], v243 offset:22528
	ds_read_b128 v[192:195], v243 offset:23552
	global_load_lds_dwordx4 v[196:197], off
	s_add_i32 m0, s12, 0x2000
	s_add_u32 s12, s40, 0x40000
	v_lshl_add_u64 v[198:199], s[40:41], 0, v[218:219]
	s_addc_u32 s13, s41, 0
	s_add_i32 s14, s15, s70
	global_load_lds_dwordx4 v[198:199], off
	v_lshl_add_u64 v[200:201], s[12:13], 0, v[2:3]
	s_mov_b32 m0, s14
	v_lshl_add_u64 v[202:203], s[56:57], 0, v[216:217]
	global_load_lds_dwordx4 v[200:201], off
	v_lshl_add_u64 v[200:201], s[12:13], 0, v[218:219]
	s_add_i32 m0, s14, 0x2000
	s_nop 0
	global_load_lds_dwordx4 v[200:201], off
	v_lshl_add_u64 v[200:201], s[56:57], 0, v[0:1]
	s_mov_b32 m0, s71
	s_nop 0
	global_load_lds_dwordx4 v[200:201], off
	s_mov_b32 m0, s80
	s_nop 0
	global_load_lds_dwordx4 v[202:203], off
	s_waitcnt vmcnt(8)
	s_waitcnt lgkmcnt(0)
	s_barrier
	s_setprio 1
	s_waitcnt lgkmcnt(0)
	v_mfma_f32_16x16x32_bf16 v[64:67], v[124:127], v[164:167], v[64:67]
	v_mfma_f32_16x16x32_bf16 v[60:63], v[136:139], v[164:167], v[60:63]
	v_mfma_f32_16x16x32_bf16 v[48:51], v[124:127], v[172:175], v[48:51]
	v_mfma_f32_16x16x32_bf16 v[44:47], v[136:139], v[172:175], v[44:47]
	v_mfma_f32_16x16x32_bf16 v[32:35], v[124:127], v[180:183], v[32:35]
	v_mfma_f32_16x16x32_bf16 v[28:31], v[136:139], v[180:183], v[28:31]
	v_mfma_f32_16x16x32_bf16 v[16:19], v[124:127], v[188:191], v[16:19]
	v_mfma_f32_16x16x32_bf16 v[12:15], v[136:139], v[188:191], v[12:15]
	v_mfma_f32_16x16x32_bf16 v[64:67], v[128:131], v[168:171], v[64:67]
	v_mfma_f32_16x16x32_bf16 v[60:63], v[144:147], v[168:171], v[60:63]
	v_mfma_f32_16x16x32_bf16 v[48:51], v[128:131], v[176:179], v[48:51]
	v_mfma_f32_16x16x32_bf16 v[44:47], v[144:147], v[176:179], v[44:47]
	v_mfma_f32_16x16x32_bf16 v[32:35], v[128:131], v[184:187], v[32:35]
	v_mfma_f32_16x16x32_bf16 v[28:31], v[144:147], v[184:187], v[28:31]
	v_mfma_f32_16x16x32_bf16 v[16:19], v[128:131], v[192:195], v[16:19]
	v_mfma_f32_16x16x32_bf16 v[12:15], v[144:147], v[192:195], v[12:15]
	s_setprio 0
	s_setprio 1
	v_mfma_f32_16x16x32_bf16 v[56:59], v[148:151], v[164:167], v[56:59]
	v_mfma_f32_16x16x32_bf16 v[52:55], v[156:159], v[164:167], v[52:55]
	v_mfma_f32_16x16x32_bf16 v[40:43], v[148:151], v[172:175], v[40:43]
	v_mfma_f32_16x16x32_bf16 v[36:39], v[156:159], v[172:175], v[36:39]
	v_mfma_f32_16x16x32_bf16 v[24:27], v[148:151], v[180:183], v[24:27]
	v_mfma_f32_16x16x32_bf16 v[20:23], v[156:159], v[180:183], v[20:23]
	v_mfma_f32_16x16x32_bf16 v[8:11], v[148:151], v[188:191], v[8:11]
	v_mfma_f32_16x16x32_bf16 v[4:7], v[156:159], v[188:191], v[4:7]
	v_mfma_f32_16x16x32_bf16 v[56:59], v[152:155], v[168:171], v[56:59]
	v_mfma_f32_16x16x32_bf16 v[52:55], v[160:163], v[168:171], v[52:55]
	v_mfma_f32_16x16x32_bf16 v[40:43], v[152:155], v[176:179], v[40:43]
	v_mfma_f32_16x16x32_bf16 v[36:39], v[160:163], v[176:179], v[36:39]
	v_mfma_f32_16x16x32_bf16 v[24:27], v[152:155], v[184:187], v[24:27]
	v_mfma_f32_16x16x32_bf16 v[20:23], v[160:163], v[184:187], v[20:23]
	v_mfma_f32_16x16x32_bf16 v[8:11], v[152:155], v[192:195], v[8:11]
	v_mfma_f32_16x16x32_bf16 v[4:7], v[160:163], v[192:195], v[4:7]
	s_setprio 0
	s_barrier
	s_add_i32 s14, 0, 0x18000
	s_add_i32 s15, 0, 0x1c000
	v_add_u32_e32 v144, s14, v230
	v_add_u32_e32 v160, s15, v230
	ds_read_b128 v[124:127], v144
	ds_read_b128 v[128:131], v144 offset:1024
	ds_read_b128 v[136:139], v144 offset:2048
	ds_read_b128 v[144:147], v144 offset:3072
	ds_read_b128 v[148:151], v160
	ds_read_b128 v[152:155], v160 offset:1024
	ds_read_b128 v[156:159], v160 offset:2048
	ds_read_b128 v[160:163], v160 offset:3072
	s_add_u32 s12, s56, 0x40000
	s_addc_u32 s13, s57, 0
	s_mov_b32 m0, s81
	v_lshl_add_u64 v[204:205], s[12:13], 0, v[0:1]
	ds_read_b128 v[164:167], v243 offset:32768
	ds_read_b128 v[168:171], v243 offset:33792
	ds_read_b128 v[172:175], v243 offset:34816
	ds_read_b128 v[176:179], v243 offset:35840
	ds_read_b128 v[180:183], v243 offset:36864
	ds_read_b128 v[184:187], v243 offset:37888
	ds_read_b128 v[188:191], v243 offset:38912
	ds_read_b128 v[192:195], v243 offset:39936
	global_load_lds_dwordx4 v[204:205], off
	v_lshl_add_u64 v[204:205], s[12:13], 0, v[216:217]
	s_mov_b32 m0, s82
	s_nop 0
	global_load_lds_dwordx4 v[204:205], off
	s_waitcnt vmcnt(8)
	s_waitcnt lgkmcnt(0)
	s_barrier
	s_setprio 1
	s_waitcnt lgkmcnt(0)
	v_mfma_f32_16x16x32_bf16 v[140:143], v[124:127], v[164:167], v[140:143]
	v_mfma_f32_16x16x32_bf16 v[132:135], v[136:139], v[164:167], v[132:135]
	v_mfma_f32_16x16x32_bf16 v[112:115], v[124:127], v[172:175], v[112:115]
	v_mfma_f32_16x16x32_bf16 v[108:111], v[136:139], v[172:175], v[108:111]
	v_mfma_f32_16x16x32_bf16 v[96:99], v[124:127], v[180:183], v[96:99]
	v_mfma_f32_16x16x32_bf16 v[92:95], v[136:139], v[180:183], v[92:95]
	v_mfma_f32_16x16x32_bf16 v[80:83], v[124:127], v[188:191], v[80:83]
	v_mfma_f32_16x16x32_bf16 v[76:79], v[136:139], v[188:191], v[76:79]
	v_mfma_f32_16x16x32_bf16 v[140:143], v[128:131], v[168:171], v[140:143]
	v_mfma_f32_16x16x32_bf16 v[132:135], v[144:147], v[168:171], v[132:135]
	v_mfma_f32_16x16x32_bf16 v[112:115], v[128:131], v[176:179], v[112:115]
	v_mfma_f32_16x16x32_bf16 v[108:111], v[144:147], v[176:179], v[108:111]
	v_mfma_f32_16x16x32_bf16 v[96:99], v[128:131], v[184:187], v[96:99]
	v_mfma_f32_16x16x32_bf16 v[92:95], v[144:147], v[184:187], v[92:95]
	v_mfma_f32_16x16x32_bf16 v[80:83], v[128:131], v[192:195], v[80:83]
	v_mfma_f32_16x16x32_bf16 v[76:79], v[144:147], v[192:195], v[76:79]
	s_setprio 0
	s_setprio 1
	v_mfma_f32_16x16x32_bf16 v[120:123], v[148:151], v[164:167], v[120:123]
	v_mfma_f32_16x16x32_bf16 v[116:119], v[156:159], v[164:167], v[116:119]
	v_mfma_f32_16x16x32_bf16 v[104:107], v[148:151], v[172:175], v[104:107]
	v_mfma_f32_16x16x32_bf16 v[100:103], v[156:159], v[172:175], v[100:103]
	v_mfma_f32_16x16x32_bf16 v[88:91], v[148:151], v[180:183], v[88:91]
	v_mfma_f32_16x16x32_bf16 v[84:87], v[156:159], v[180:183], v[84:87]
	v_mfma_f32_16x16x32_bf16 v[72:75], v[148:151], v[188:191], v[72:75]
	v_mfma_f32_16x16x32_bf16 v[68:71], v[156:159], v[188:191], v[68:71]
	v_mfma_f32_16x16x32_bf16 v[120:123], v[152:155], v[168:171], v[120:123]
	v_mfma_f32_16x16x32_bf16 v[116:119], v[160:163], v[168:171], v[116:119]
	v_mfma_f32_16x16x32_bf16 v[104:107], v[152:155], v[176:179], v[104:107]
	v_mfma_f32_16x16x32_bf16 v[100:103], v[160:163], v[176:179], v[100:103]
	v_mfma_f32_16x16x32_bf16 v[88:91], v[152:155], v[184:187], v[88:91]
	v_mfma_f32_16x16x32_bf16 v[84:87], v[160:163], v[184:187], v[84:87]
	v_mfma_f32_16x16x32_bf16 v[72:75], v[152:155], v[192:195], v[72:75]
	v_mfma_f32_16x16x32_bf16 v[68:71], v[160:163], v[192:195], v[68:71]
	s_setprio 0
	s_barrier
	s_add_i32 s12, s14, s70
	v_lshl_add_u64 v[196:197], v[196:197], 0, s[68:69]
	s_mov_b32 m0, s12
	ds_read_b128 v[164:167], v243 offset:49152
	ds_read_b128 v[168:171], v243 offset:50176
	ds_read_b128 v[172:175], v243 offset:51200
	ds_read_b128 v[176:179], v243 offset:52224
	ds_read_b128 v[180:183], v243 offset:53248
	ds_read_b128 v[184:187], v243 offset:54272
	ds_read_b128 v[188:191], v243 offset:55296
	ds_read_b128 v[192:195], v243 offset:56320
	global_load_lds_dwordx4 v[196:197], off
	s_add_i32 m0, s12, 0x2000
	s_add_u32 s12, s40, 0x40080
	v_lshl_add_u64 v[196:197], v[198:199], 0, s[68:69]
	s_addc_u32 s13, s41, 0
	s_add_i32 s14, s15, s70
	global_load_lds_dwordx4 v[196:197], off
	v_lshl_add_u64 v[196:197], s[12:13], 0, v[2:3]
	s_mov_b32 m0, s14
	s_nop 0
	global_load_lds_dwordx4 v[196:197], off
	v_lshl_add_u64 v[196:197], s[12:13], 0, v[218:219]
	s_add_i32 m0, s14, 0x2000
	s_nop 0
	global_load_lds_dwordx4 v[196:197], off
	v_lshl_add_u64 v[196:197], v[200:201], 0, s[68:69]
	s_mov_b32 m0, s85
	s_nop 0
	global_load_lds_dwordx4 v[196:197], off
	v_lshl_add_u64 v[196:197], v[202:203], 0, s[68:69]
	s_mov_b32 m0, s87
	s_nop 0
	global_load_lds_dwordx4 v[196:197], off
	s_waitcnt vmcnt(8)
	s_waitcnt lgkmcnt(0)
	s_barrier
	s_setprio 1
	s_waitcnt lgkmcnt(0)
	v_mfma_f32_16x16x32_bf16 v[64:67], v[124:127], v[164:167], v[64:67]
	v_mfma_f32_16x16x32_bf16 v[60:63], v[136:139], v[164:167], v[60:63]
	v_mfma_f32_16x16x32_bf16 v[48:51], v[124:127], v[172:175], v[48:51]
	v_mfma_f32_16x16x32_bf16 v[44:47], v[136:139], v[172:175], v[44:47]
	v_mfma_f32_16x16x32_bf16 v[32:35], v[124:127], v[180:183], v[32:35]
	v_mfma_f32_16x16x32_bf16 v[28:31], v[136:139], v[180:183], v[28:31]
	v_mfma_f32_16x16x32_bf16 v[16:19], v[124:127], v[188:191], v[16:19]
	v_mfma_f32_16x16x32_bf16 v[12:15], v[136:139], v[188:191], v[12:15]
	v_mfma_f32_16x16x32_bf16 v[64:67], v[128:131], v[168:171], v[64:67]
	v_mfma_f32_16x16x32_bf16 v[60:63], v[144:147], v[168:171], v[60:63]
	v_mfma_f32_16x16x32_bf16 v[48:51], v[128:131], v[176:179], v[48:51]
	v_mfma_f32_16x16x32_bf16 v[44:47], v[144:147], v[176:179], v[44:47]
	v_mfma_f32_16x16x32_bf16 v[32:35], v[128:131], v[184:187], v[32:35]
	v_mfma_f32_16x16x32_bf16 v[28:31], v[144:147], v[184:187], v[28:31]
	v_mfma_f32_16x16x32_bf16 v[16:19], v[128:131], v[192:195], v[16:19]
	v_mfma_f32_16x16x32_bf16 v[12:15], v[144:147], v[192:195], v[12:15]
	s_setprio 0
	s_setprio 1
	v_mfma_f32_16x16x32_bf16 v[56:59], v[148:151], v[164:167], v[56:59]
	v_mfma_f32_16x16x32_bf16 v[52:55], v[156:159], v[164:167], v[52:55]
	v_mfma_f32_16x16x32_bf16 v[40:43], v[148:151], v[172:175], v[40:43]
	v_mfma_f32_16x16x32_bf16 v[36:39], v[156:159], v[172:175], v[36:39]
	v_mfma_f32_16x16x32_bf16 v[24:27], v[148:151], v[180:183], v[24:27]
	v_mfma_f32_16x16x32_bf16 v[20:23], v[156:159], v[180:183], v[20:23]
	v_mfma_f32_16x16x32_bf16 v[8:11], v[148:151], v[188:191], v[8:11]
	v_mfma_f32_16x16x32_bf16 v[4:7], v[156:159], v[188:191], v[4:7]
	v_mfma_f32_16x16x32_bf16 v[56:59], v[152:155], v[168:171], v[56:59]
	v_mfma_f32_16x16x32_bf16 v[52:55], v[160:163], v[168:171], v[52:55]
	v_mfma_f32_16x16x32_bf16 v[40:43], v[152:155], v[176:179], v[40:43]
	v_mfma_f32_16x16x32_bf16 v[36:39], v[160:163], v[176:179], v[36:39]
	v_mfma_f32_16x16x32_bf16 v[24:27], v[152:155], v[184:187], v[24:27]
	v_mfma_f32_16x16x32_bf16 v[20:23], v[160:163], v[184:187], v[20:23]
	v_mfma_f32_16x16x32_bf16 v[8:11], v[152:155], v[192:195], v[8:11]
	v_mfma_f32_16x16x32_bf16 v[4:7], v[160:163], v[192:195], v[4:7]
	s_setprio 0
	s_barrier
	s_add_i32 s11, s11, 2
	s_add_u32 s9, s9, 0x100
	s_addc_u32 s10, s10, 0
	s_add_u32 s38, s38, 0x100
	s_addc_u32 s39, s39, 0
	s_cmp_gt_u32 s11, 13
	s_cbranch_scc0 .LBB0_947
	s_lshl_b32 s98, s20, 8
	s_or_b32 s98, s98, s84
	s_lshl_b32 s99, s4, 8
	s_add_i32 s99, s99, s83
	v_ashrrev_i32_e32 v136, 1, v234
	v_and_b32_e32 v137, 15, v234
	v_and_b32_e32 v136, -8, v136
	v_add_u32_e32 v137, s99, v137
	v_add_u32_e32 v136, s98, v136
	v_lshlrev_b32_e32 v136, 1, v136
	v_lshl_add_u32 v212, v137, 12, v136
	global_load_dwordx4 v[208:211], v212, s[24:25]
	global_load_dwordx4 v[204:207], v212, s[24:25] offset:256
	s_add_u32 s100, s24, 0x10000
	s_addc_u32 s101, s25, 0
	global_load_dwordx4 v[200:203], v212, s[100:101]
	global_load_dwordx4 v[196:199], v212, s[100:101] offset:256
	s_add_u32 s100, s24, 0x20000
	s_addc_u32 s101, s25, 0
	global_load_dwordx4 v[192:195], v212, s[100:101]
	global_load_dwordx4 v[188:191], v212, s[100:101] offset:256
	s_add_u32 s100, s24, 0x30000
	s_addc_u32 s101, s25, 0
	global_load_dwordx4 v[184:187], v212, s[100:101]
	global_load_dwordx4 v[180:183], v212, s[100:101] offset:256
	s_add_u32 s100, s24, 0x80000
	s_addc_u32 s101, s25, 0
	global_load_dwordx4 v[176:179], v212, s[100:101]
	global_load_dwordx4 v[172:175], v212, s[100:101] offset:256
	s_add_u32 s100, s24, 0x90000
	s_addc_u32 s101, s25, 0
	global_load_dwordx4 v[168:171], v212, s[100:101]
	global_load_dwordx4 v[164:167], v212, s[100:101] offset:256
	s_add_u32 s100, s24, 0xa0000
	s_addc_u32 s101, s25, 0
	global_load_dwordx4 v[160:163], v212, s[100:101]
	global_load_dwordx4 v[156:159], v212, s[100:101] offset:256
	s_add_u32 s100, s24, 0xb0000
	s_addc_u32 s101, s25, 0
	global_load_dwordx4 v[152:155], v212, s[100:101]
	global_load_dwordx4 v[148:151], v212, s[100:101] offset:256
	s_and_b64 vcc, exec, s[46:47]
	s_cbranch_vccz .LBB0_950
	s_barrier

.LBB0_970:
	s_or_b64 exec, exec, s[56:57]
	s_lshl_b32 s4, s20, 8
	v_ashrrev_i32_e32 v124, 1, v246
	v_and_b32_e32 v248, 15, v246
	v_and_b32_e32 v124, -8, v124
	s_or_b32 s4, s4, s84
	v_add_u32_e32 v226, s4, v124
	v_ashrrev_i32_e32 v227, 31, v226
	v_lshl_add_u64 v[128:129], v[226:227], 2, s[26:27]
	global_load_dwordx4 v[136:139], v[128:129], off offset:16
	global_load_dwordx4 v[144:147], v[128:129], off
	s_waitcnt lgkmcnt(0)
	global_load_dwordx4 v[124:127], v[128:129], off offset:528
	s_nop 0
	global_load_dwordx4 v[128:131], v[128:129], off offset:512
	s_nop 0
	s_nop 0
	v_ashrrev_i32_e32 v214, 3, v246
	v_and_b32_e32 v214, -4, v214
	v_lshl_add_u64 v[212:213], s[42:43], 0, v[224:225]
	v_ashrrev_i32_e32 v215, 31, v214
	v_lshl_add_u64 v[228:229], v[214:215], 2, v[212:213]
	s_movk_i32 s4, 0x4e20
	s_branch .LBB0_973
